# sched 10/21: stack4 + decode slot classes 10/11/11 per 32 CUs instead of 11/11/10 (one CU per group moved from the first decode window to the second)
# baseline (speedup 1.0000x reference)
.LBB0_377:
	v_readlane_b32 s8, v247, 12
	s_and_b32 s1, s8, 31
	s_cmp_gt_u32 s1, 9
	s_cselect_b32 s2, 1, 0
	s_cmp_gt_u32 s1, 20
	s_cselect_b32 s3, 1, 0
	s_cmp_gt_u32 s1, 31
	s_cselect_b32 s4, 1, 0
	s_add_i32 s1, s2, s3
	s_sub_i32 s1, s1, s4
	s_and_b32 s9, s8, 15
	s_ashr_i32 s0, s8, 7
	s_cmp_lg_u32 s1, 1
	s_cselect_b64 s[2:3], -1, 0
	s_bitcmp1_b32 s8, 4
	s_cselect_b64 s[4:5], -1, 0
	v_writelane_b32 v247, s1, 37
	s_mov_b32 s1, 0xdc00000
	s_and_b64 s[6:7], s[4:5], exec
	s_cselect_b32 s1, s1, 0xcc00000
	s_or_b64 s[2:3], s[2:3], s[4:5]
	v_writelane_b32 v247, s2, 40
	s_cmpk_lt_i32 s8, 0x200
	s_mov_b32 s65, 0
	v_writelane_b32 v247, s3, 41
	s_cselect_b64 s[2:3], -1, 0
	v_writelane_b32 v247, s2, 42
	v_mov_b32_e32 v2, 0
	s_movk_i32 s79, 0x1000
	v_writelane_b32 v247, s3, 43
	v_writelane_b32 v247, s9, 44
	s_xor_b32 s2, s9, 31
	v_writelane_b32 v247, s2, 45
	s_add_u32 s2, s92, s1
	s_addc_u32 s3, s93, 0
	s_ashr_i32 s1, s0, 31
	s_lshl_b64 s[4:5], s[0:1], 13
	v_writelane_b32 v247, s4, 46
	s_mov_b32 s80, 0x41000000
	s_mov_b32 s81, 0xff800000
	v_writelane_b32 v247, s5, 47
	s_and_b32 s4, s95, 0x380
	v_readlane_b32 s5, v247, 24
	s_add_u32 s30, s5, s4
	v_readlane_b32 s5, v247, 26
	s_addc_u32 s31, s5, 0
	s_lshl_b64 s[0:1], s[0:1], 23
	s_add_u32 s5, s82, s0
	s_addc_u32 s6, s83, s1
	s_add_u32 s4, s5, s4
	s_addc_u32 s5, s6, 0
	v_writelane_b32 v247, s4, 24
	v_mov_b32_e32 v224, 0x3727c5ac
	v_mov_b32_e32 v225, 0x260
	v_writelane_b32 v247, s5, 25
	s_mov_b64 s[82:83], 0x20000
	v_readlane_b32 s4, v247, 27
	s_add_u32 s4, s4, s0
	v_readlane_b32 s5, v247, 29
	s_addc_u32 s5, s5, s1
	s_and_b32 s6, s95, 0x300
	s_add_u32 s4, s4, s6
	s_addc_u32 s5, s5, 0
	v_writelane_b32 v247, s4, 27
	s_add_u32 s34, s2, s6
	s_addc_u32 s35, s3, 0
	v_writelane_b32 v247, s5, 28
	s_and_b32 s2, s8, 0xffffffe0
	v_writelane_b32 v247, s2, 48
	s_add_u32 s2, s92, 0xc000
	v_writelane_b32 v247, s2, 49
	s_addc_u32 s2, s93, 0
	v_writelane_b32 v247, s2, 50
	s_add_u32 s2, s92, 0xbc00
	s_addc_u32 s3, s93, 0
	v_writelane_b32 v247, s2, 51
	s_mov_b64 s[76:77], 0x40000
	s_mov_b64 s[90:91], 0x5820000
	v_writelane_b32 v247, s3, 52
	s_add_u32 s2, s92, 0x4800
	s_addc_u32 s3, s93, 0
	s_or_b32 s0, s0, s6
	v_writelane_b32 v247, s2, 53
	s_add_u32 s0, s92, s0
	s_addc_u32 s1, s93, s1
	v_writelane_b32 v247, s3, 54
	v_writelane_b32 v247, s0, 29
	s_add_i32 s62, 0, 0x1a800
	s_mov_b64 s[92:93], 0x5820080
	v_writelane_b32 v247, s1, 30
	v_mov_b32_e32 v226, 1
	v_readlane_b32 s68, v247, 20
	v_readlane_b32 s69, v247, 21
	v_readlane_b32 s70, v247, 22
	v_readlane_b32 s71, v247, 23
	v_writelane_b32 v247, s30, 55
	v_writelane_b32 v247, s31, 26
	v_writelane_b32 v247, s34, 56
	v_mov_b32_e32 v227, 0xff800000
	v_mov_b32_e32 v228, 0x7f800000
	v_mov_b32_e32 v229, 0x3e4ccccd
	s_mov_b32 s88, 0
	v_writelane_b32 v247, s35, 57
	v_writelane_b32 v247, s62, 58
	s_branch .LBB0_381
